# GEMM start stagger selected by bit 0 of the workgroup id (odd XCDs) instead of bit 3
# baseline (speedup 1.0000x reference)
; #define LAS __attribute__((address_space(3)))
; __device__ __forceinline__ unsigned xb_add(unsigned* p, unsigned v) { return __hip_atomic_fetch_add(p, v, __ATOMIC_RELAXED, __HIP_MEMORY_SCOPE_AGENT); }
; __device__ __forceinline__ unsigned xb_xcc_id() { return (unsigned)__builtin_amdgcn_s_getreg((3 << 11) | 20) & 0xFu; }
; __device__ __forceinline__ XcdBarrier xcd_barrier_post(unsigned* bar, volatile LAS unsigned* st) {
;     XcdBarrier b; b.bar = bar; b.x = xb_xcc_id(); b.st = st;
;     if (threadIdx.x == 0) (void)xb_add(&bar[XB_XCNT(b.x)], 1u);
;     return b;
; }
; __global__ void __launch_bounds__(NWAVES * 64, 2) hymba_fwd(Args A) {
;     ...
;     grid.sync();
;     XcdBarrier bar = xcd_barrier_post((unsigned*)ws, bst);
;     {
;         pg8::Gemm g{(const pg8::bf16_t*)(ws + WS_XA), (const pg8::bf16_t*)(ws + WS_W1), M1, DIN, DM, DM};
;         pg8::StaticOrder S; S.init(M1, DIN, G, bx);
;         pg8::Epi1 E{(const float*)(ws + WS_RS1), (const float*)(ws + WS_ROPE), A.out, (pg8::bf16_t*)(ws + WS_QD), (pg8::bf16_t*)(ws + WS_QS), (pg8::bf16_t*)(ws + WS_KD), (pg8::bf16_t*)(ws + WS_KS),
;                     (pg8::bf16_t*)(ws + WS_VDT), (pg8::bf16_t*)(ws + WS_VST)};
;         pg8::gemm_phase<pg8::Epi1, pg8::StaticOrder, true, true>(lds, g, S, E);
.LBB0_102:
	s_or_b64 exec, exec, s[0:1]
	s_barrier
	s_cmp_lt_u32 s22, 36
	s_cbranch_scc1 .Lstag_p1
	s_bitcmp1_b32 s22, 0
	s_cbranch_scc0 .Lstag_p1
	s_sleep 127
	s_sleep 127
	s_sleep 127

; __global__ void __launch_bounds__(NWAVES * 64, 2) hymba_fwd(Args A) {
;     ...
;         pg8::Gemm g{(const pg8::bf16_t*)(ws + WS_X1B), (const pg8::bf16_t*)(ws + WS_W3), M2, DFF, DM, DM};
;         pg8::StaticOrder S; S.init(M2, DFF, G, bx);
;         pg8::Epi3 E{(const float*)(ws + WS_SS2), (pg8::bf16_t*)(ws + WS_H)};
;         pg8::gemm_phase<pg8::Epi3, pg8::StaticOrder, true, true>(lds, g, S, E);
.LBB0_746:
	s_or_b64 exec, exec, s[0:1]
	v_mov_b32_e32 v9, v138
	s_waitcnt lgkmcnt(0)
	s_barrier
	s_cmp_lt_u32 s22, 32
	s_cbranch_scc1 .Lstag_p4
	s_bitcmp1_b32 s22, 0
	s_cbranch_scc0 .Lstag_p4
	s_sleep 127
	s_sleep 127
	s_sleep 127
